# in-proj: row-ssq values prefetched into phase-free VGPRs at tile start; epilogue no longer drains the next-tile DMA prefetch before computing rstd
# speedup vs baseline: 1.0068x; 1.0024x over previous
;     DI void operator()(const f32x4 (&acc)[2][2][4][2], const Unit& u, int wr, int wc, int fr, int fq) const {
;         int row0 = u.pm * BM + wr * 64 + fr, col0 = u.pn * BM + wc * 32 + 8 * fq;
;         asm volatile("" : "+v"(row0), "+v"(col0));
;         float rstd[2][4];
; #pragma unroll
;         for (int ai = 0; ai < 2; ++ai)
; #pragma unroll
;             for (int m = 0; m < 4; ++m) rstd[ai][m] = rsqrtf(ssq[row0 + ai * HALF + m * 16] * (1.0f / DM) + EPS);
; template <class Epi, class Sched>
; DI void gemm_phase(LAS unsigned char* lds, const int tid, const int K, const int lda, const int ldb, const Sched& S_, const Epi& E) {
;     ...
;     f32x4 acc[2][2][4][2];
; #pragma unroll
;     for (int a = 0; a < 2; ++a)
; #pragma unroll
;         for (int b = 0; b < 2; ++b)
; #pragma unroll
;             for (int m = 0; m < 4; ++m)
; #pragma unroll
;                 for (int n = 0; n < 2; ++n) acc[a][b][m][n] = (f32x4){0.f, 0.f, 0.f, 0.f};
.LBB0_129:
	v_lshl_add_u32 v246, s2, 8, v147
	v_ashrrev_i32_e32 v247, 31, v246
	v_lshl_add_u64 v[246:247], v[246:247], 2, s[58:59]
	global_load_dword v238, v[246:247], off
	global_load_dword v239, v[246:247], off offset:64
	global_load_dword v240, v[246:247], off offset:128
	global_load_dword v241, v[246:247], off offset:192
	global_load_dword v242, v[246:247], off offset:512
	global_load_dword v243, v[246:247], off offset:576
	global_load_dword v244, v[246:247], off offset:640
	global_load_dword v245, v[246:247], off offset:704
	s_add_u32 s4, s4, 0x80080
	s_addc_u32 s5, s5, 0
	s_add_u32 s3, s6, 0x100
	v_mov_b32_e32 v0, 0
	s_addc_u32 s11, s7, 0
	s_mov_b32 s14, -2
	v_mov_b32_e32 v1, v0
	v_mov_b32_e32 v2, v0
	v_mov_b32_e32 v3, v0
	v_mov_b32_e32 v4, v0
	v_mov_b32_e32 v5, v0
	v_mov_b32_e32 v6, v0
	v_mov_b32_e32 v7, v0
	v_mov_b32_e32 v16, v0
	v_mov_b32_e32 v17, v0
	v_mov_b32_e32 v18, v0
	v_mov_b32_e32 v19, v0
	v_mov_b32_e32 v20, v0
	v_mov_b32_e32 v21, v0
	v_mov_b32_e32 v22, v0
	v_mov_b32_e32 v23, v0
	v_mov_b32_e32 v32, v0
	v_mov_b32_e32 v33, v0
	v_mov_b32_e32 v34, v0
	v_mov_b32_e32 v35, v0
	v_mov_b32_e32 v36, v0
	v_mov_b32_e32 v37, v0
	v_mov_b32_e32 v38, v0
	v_mov_b32_e32 v39, v0
	v_mov_b32_e32 v48, v0
	v_mov_b32_e32 v49, v0
	v_mov_b32_e32 v50, v0
	v_mov_b32_e32 v51, v0
	v_mov_b32_e32 v52, v0
	v_mov_b32_e32 v53, v0
	v_mov_b32_e32 v54, v0
	v_mov_b32_e32 v55, v0
	v_mov_b32_e32 v8, v0
	v_mov_b32_e32 v9, v0
	v_mov_b32_e32 v10, v0
	v_mov_b32_e32 v11, v0
	v_mov_b32_e32 v12, v0
	v_mov_b32_e32 v13, v0
	v_mov_b32_e32 v14, v0
	v_mov_b32_e32 v15, v0
	v_mov_b32_e32 v24, v0
	v_mov_b32_e32 v25, v0
	v_mov_b32_e32 v26, v0
	v_mov_b32_e32 v27, v0
	v_mov_b32_e32 v28, v0
	v_mov_b32_e32 v29, v0
	v_mov_b32_e32 v30, v0
	v_mov_b32_e32 v31, v0
	v_mov_b32_e32 v40, v0
	v_mov_b32_e32 v41, v0
	v_mov_b32_e32 v42, v0
	v_mov_b32_e32 v43, v0
	v_mov_b32_e32 v44, v0
	v_mov_b32_e32 v45, v0
	v_mov_b32_e32 v46, v0
	v_mov_b32_e32 v47, v0
	v_mov_b32_e32 v56, v0
	v_mov_b32_e32 v57, v0
	v_mov_b32_e32 v58, v0
	v_mov_b32_e32 v59, v0
	v_mov_b32_e32 v60, v0
	v_mov_b32_e32 v61, v0
	v_mov_b32_e32 v62, v0
	v_mov_b32_e32 v63, v0
	v_mov_b32_e32 v64, v0
	v_mov_b32_e32 v65, v0
	v_mov_b32_e32 v66, v0
	v_mov_b32_e32 v67, v0
	v_mov_b32_e32 v68, v0
	v_mov_b32_e32 v69, v0
	v_mov_b32_e32 v70, v0
	v_mov_b32_e32 v71, v0
	v_mov_b32_e32 v80, v0
	v_mov_b32_e32 v81, v0
	v_mov_b32_e32 v82, v0
	v_mov_b32_e32 v83, v0
	v_mov_b32_e32 v84, v0
	v_mov_b32_e32 v85, v0
	v_mov_b32_e32 v86, v0
	v_mov_b32_e32 v87, v0
	v_mov_b32_e32 v96, v0
	v_mov_b32_e32 v97, v0
	v_mov_b32_e32 v98, v0
	v_mov_b32_e32 v99, v0
	v_mov_b32_e32 v100, v0
	v_mov_b32_e32 v101, v0
	v_mov_b32_e32 v102, v0
	v_mov_b32_e32 v103, v0
	v_mov_b32_e32 v112, v0
	v_mov_b32_e32 v113, v0
	v_mov_b32_e32 v114, v0
	v_mov_b32_e32 v115, v0
	v_mov_b32_e32 v116, v0
	v_mov_b32_e32 v117, v0
	v_mov_b32_e32 v118, v0
	v_mov_b32_e32 v119, v0
	v_mov_b32_e32 v72, v0
	v_mov_b32_e32 v73, v0
	v_mov_b32_e32 v74, v0
	v_mov_b32_e32 v75, v0
	v_mov_b32_e32 v76, v0
	v_mov_b32_e32 v77, v0
	v_mov_b32_e32 v78, v0
	v_mov_b32_e32 v79, v0
	v_mov_b32_e32 v88, v0
	v_mov_b32_e32 v89, v0
	v_mov_b32_e32 v90, v0
	v_mov_b32_e32 v91, v0
	v_mov_b32_e32 v92, v0
	v_mov_b32_e32 v93, v0
	v_mov_b32_e32 v94, v0
	v_mov_b32_e32 v95, v0
	v_mov_b32_e32 v104, v0
	v_mov_b32_e32 v105, v0
	v_mov_b32_e32 v106, v0
	v_mov_b32_e32 v107, v0
	v_mov_b32_e32 v108, v0
	v_mov_b32_e32 v109, v0
	v_mov_b32_e32 v110, v0
	v_mov_b32_e32 v111, v0
	v_mov_b32_e32 v120, v0
	v_mov_b32_e32 v121, v0
	v_mov_b32_e32 v122, v0
	v_mov_b32_e32 v123, v0
	v_mov_b32_e32 v124, v0
	v_mov_b32_e32 v125, v0
	v_mov_b32_e32 v126, v0
	v_mov_b32_e32 v127, v0

;     DI void operator()(const f32x4 (&acc)[2][2][4][2], const Unit& u, int wr, int wc, int fr, int fq) const {
;         int row0 = u.pm * BM + wr * 64 + fr, col0 = u.pn * BM + wc * 32 + 8 * fq;
;         asm volatile("" : "+v"(row0), "+v"(col0));
;         float rstd[2][4];
; #pragma unroll
;         for (int ai = 0; ai < 2; ++ai)
; #pragma unroll
;             for (int m = 0; m < 4; ++m) rstd[ai][m] = rsqrtf(ssq[row0 + ai * HALF + m * 16] * (1.0f / DM) + EPS);
;         if (u.pn < NHT) {
;             const int hs = 4 * u.pn + wc;
;             if (hs >= 74) return;
;     ...
; #pragma unroll
;         for (int bj = 0; bj < 2; ++bj) {
;             const int colw = u.pn * BM + bj * HALF + wc * 32;
;             const int act = colw < C_SILU ? 0 : (colw < C_GATE ? 1 : 2);
.LBB0_133:
	s_lshl_b32 s4, s10, 8
	v_lshl_add_u32 v170, s2, 8, v147
	v_or_b32_e32 v130, s4, v197
	s_mov_b64 s[2:3], -1
	v_ashrrev_i32_e32 v171, 31, v170
	v_lshl_add_u64 v[132:133], v[170:171], 2, s[58:59]
	v_add_u32_e32 v222, 16, v170
	v_add_u32_e32 v211, 32, v170
	v_add_u32_e32 v209, 48, v170
	v_add_u32_e32 v207, 0x80, v170
	v_add_u32_e32 v205, 0x90, v170
	v_add_u32_e32 v203, 0xa0, v170
	v_add_u32_e32 v201, 0xb0, v170
	v_ashrrev_i32_e32 v223, 31, v222
	v_ashrrev_i32_e32 v221, 31, v211
	v_ashrrev_i32_e32 v210, 31, v209
	v_ashrrev_i32_e32 v208, 31, v207
	v_ashrrev_i32_e32 v206, 31, v205
	v_ashrrev_i32_e32 v204, 31, v203
	v_ashrrev_i32_e32 v202, 31, v201
	s_cmp_lt_i32 s10, 19
	v_fmamk_f32 v172, v238, 0x3a000000, v218
	v_cmp_gt_f32_e32 vcc, s33, v172
	v_mul_f32_e32 v131, 0x4b800000, v172
	s_nop 0
	v_cndmask_b32_e32 v172, v172, v131, vcc
	v_rsq_f32_e32 v172, v172
	s_nop 0
	v_mul_f32_e32 v131, 0x45800000, v172
	v_cndmask_b32_e32 v172, v172, v131, vcc
	v_fmamk_f32 v168, v239, 0x3a000000, v218
	v_cmp_gt_f32_e32 vcc, s33, v168
	v_mul_f32_e32 v131, 0x4b800000, v168
	s_nop 0
	v_cndmask_b32_e32 v168, v168, v131, vcc
	v_rsq_f32_e32 v168, v168
	s_nop 0
	v_mul_f32_e32 v131, 0x45800000, v168
	v_cndmask_b32_e32 v168, v168, v131, vcc
	v_fmamk_f32 v166, v240, 0x3a000000, v218
	v_cmp_gt_f32_e32 vcc, s33, v166
	v_mul_f32_e32 v131, 0x4b800000, v166
	s_nop 0
	v_cndmask_b32_e32 v166, v166, v131, vcc
	v_rsq_f32_e32 v166, v166
	s_nop 0
	v_mul_f32_e32 v131, 0x45800000, v166
	v_cndmask_b32_e32 v166, v166, v131, vcc
	v_fmamk_f32 v164, v241, 0x3a000000, v218
	v_cmp_gt_f32_e32 vcc, s33, v164
	v_mul_f32_e32 v131, 0x4b800000, v164
	s_nop 0
	v_cndmask_b32_e32 v164, v164, v131, vcc
	v_rsq_f32_e32 v164, v164
	s_nop 0
	v_mul_f32_e32 v131, 0x45800000, v164
	v_cndmask_b32_e32 v164, v164, v131, vcc
	v_fmamk_f32 v162, v242, 0x3a000000, v218
	v_cmp_gt_f32_e32 vcc, s33, v162
	v_mul_f32_e32 v131, 0x4b800000, v162
	s_nop 0
	v_cndmask_b32_e32 v162, v162, v131, vcc
	v_rsq_f32_e32 v162, v162
	s_nop 0
	v_mul_f32_e32 v131, 0x45800000, v162
	v_cndmask_b32_e32 v162, v162, v131, vcc
	v_fmamk_f32 v160, v243, 0x3a000000, v218
	v_cmp_gt_f32_e32 vcc, s33, v160
	v_mul_f32_e32 v131, 0x4b800000, v160
	s_nop 0
	v_cndmask_b32_e32 v160, v160, v131, vcc
	v_rsq_f32_e32 v160, v160
	s_nop 0
	v_mul_f32_e32 v131, 0x45800000, v160
	v_cndmask_b32_e32 v160, v160, v131, vcc
	v_fmamk_f32 v158, v244, 0x3a000000, v218
	v_cmp_gt_f32_e32 vcc, s33, v158
	v_mul_f32_e32 v131, 0x4b800000, v158
	s_nop 0
	v_cndmask_b32_e32 v158, v158, v131, vcc
	v_rsq_f32_e32 v158, v158
	s_nop 0
	v_mul_f32_e32 v131, 0x45800000, v158
	v_cndmask_b32_e32 v158, v158, v131, vcc
	v_fmamk_f32 v128, v245, 0x3a000000, v218
	v_cmp_gt_f32_e32 vcc, s33, v128
	v_mul_f32_e32 v131, 0x4b800000, v128
	s_nop 0
	v_cndmask_b32_e32 v128, v128, v131, vcc
	v_rsq_f32_e32 v128, v128
	s_nop 0
	v_mul_f32_e32 v131, 0x45800000, v128
	v_cndmask_b32_e32 v156, v128, v131, vcc
	s_cbranch_scc1 .LBB0_199
	s_or_b32 s8, s4, s83
	s_cmpk_lt_i32 s8, 0x1da0
	s_cselect_b64 s[2:3], -1, 0
	s_cmpk_lt_i32 s8, 0x25a0
	s_cselect_b64 s[6:7], -1, 0
	s_cmpk_gt_i32 s8, 0x1d9f
	v_pk_mul_f32 v[134:135], v[124:125], v[172:173] op_sel_hi:[1,0]
	v_pk_mul_f32 v[132:133], v[120:121], v[172:173] op_sel_hi:[1,0]
	v_pk_mul_f32 v[136:137], v[126:127], v[172:173] op_sel_hi:[1,0]
	v_pk_mul_f32 v[174:175], v[122:123], v[172:173] op_sel_hi:[1,0]
	s_mov_b64 s[4:5], -1
	s_cbranch_scc1 .LBB0_136
	s_mov_b64 s[4:5], 0
